# recurrence operands fetched three steps ahead (third register set), pair operands issued early in the even step
# speedup vs baseline: 1.0046x; 1.0017x over previous
.LBB0_682:
	s_bitcmp1_b32 s30, 0
	s_cselect_b32 s6, 0xe000, 0
	s_add_i32 s6, s6, 0
	v_add_u32_e32 v90, s6, v58
	v_sub_u32_e32 v88, v90, v61
	v_add_u32_e32 v89, s6, v86
	ds_read_b128 v[4:7], v90 offset:0x4000
	ds_read_b128 v[8:11], v90 offset:0x0
	ds_read2st64_b32 v[108:109], v89 offset0:192 offset1:193
	ds_read2st64_b64 v[100:103], v88 offset0:64 offset1:65
	ds_read_b128 v[112:115], v90 offset:0x4200
	ds_read_b128 v[96:99], v90 offset:0x200
	ds_read_b128 v[120:123], v90 offset:0x4400
	ds_read_b128 v[124:127], v90 offset:0x400
	v_mov_b32_e32 v93, v91
	s_waitcnt lgkmcnt(5)
	v_pk_mul_f32 v[0:1], v[52:53], v[4:5] op_sel_hi:[0,1]
	v_pk_fma_f32 v[0:1], v[52:53], v[6:7], v[0:1] op_sel:[1,0,0]
	v_pk_mul_f32 v[10:11], v[108:109], v[10:11] op_sel_hi:[0,1]
	ds_read_b128 v[4:7], v90 offset:0x4600
	v_add_f32_dpp v0, v0, v0 quad_perm:[1,0,3,2] row_mask:0xf bank_mask:0xf bound_ctrl:1
	v_add_f32_dpp v1, v1, v1 quad_perm:[1,0,3,2] row_mask:0xf bank_mask:0xf bound_ctrl:1
	v_pk_fma_f32 v[54:55], v[52:53], v[8:9], v[10:11]
	v_add_f32_dpp v0, v0, v0 quad_perm:[2,3,0,1] row_mask:0xf bank_mask:0xf bound_ctrl:1
	ds_read_b128 v[8:11], v90 offset:0x600
	s_nop 0
	v_add_f32_dpp v0, v0, v0 row_half_mirror row_mask:0xf bank_mask:0xf bound_ctrl:1
	ds_read2st64_b32 v[110:111], v89 offset0:194 offset1:195
	ds_read2st64_b64 v[104:107], v88 offset0:66 offset1:67
	v_add_f32_dpp v2, v0, v0 row_mirror row_mask:0xf bank_mask:0xf bound_ctrl:1
	v_add_f32_dpp v0, v0, v0 row_mirror row_mask:0xf bank_mask:0xf bound_ctrl:1
	s_nop 0
	s_waitcnt lgkmcnt(6)
	v_permlane16_swap_b32_e32 v0, v2
	v_add_f32_e32 v0, v0, v2
	v_pk_fma_f32 v[52:53], v[100:101], v[0:1], v[54:55] op_sel_hi:[1,0,1]
	v_pk_mul_f32 v[118:119], v[52:53], v[112:113] op_sel_hi:[0,1]
	v_pk_fma_f32 v[118:119], v[52:53], v[114:115], v[118:119] op_sel:[1,0,0]
	v_pk_mul_f32 v[98:99], v[108:109], v[98:99] op_sel:[1,0]
	ds_read_b128 v[112:115], v90 offset:0x4800
	v_add_f32_dpp v118, v118, v118 quad_perm:[1,0,3,2] row_mask:0xf bank_mask:0xf bound_ctrl:1
	v_add_f32_dpp v119, v119, v119 quad_perm:[1,0,3,2] row_mask:0xf bank_mask:0xf bound_ctrl:1
	v_pk_fma_f32 v[54:55], v[52:53], v[96:97], v[98:99]
	v_add_f32_dpp v118, v118, v118 quad_perm:[2,3,0,1] row_mask:0xf bank_mask:0xf bound_ctrl:1
	ds_read_b128 v[96:99], v90 offset:0x800
	s_nop 0
	v_add_f32_dpp v118, v118, v118 row_half_mirror row_mask:0xf bank_mask:0xf bound_ctrl:1
	ds_write2_b32 v93, v1, v119 offset0:0 offset1:36
	s_nop 0
	v_add_f32_dpp v2, v118, v118 row_mirror row_mask:0xf bank_mask:0xf bound_ctrl:1
	v_add_f32_dpp v118, v118, v118 row_mirror row_mask:0xf bank_mask:0xf bound_ctrl:1
	s_nop 0
	s_waitcnt lgkmcnt(4)
	v_permlane16_swap_b32_e32 v118, v2
	v_add_f32_e32 v118, v118, v2
	v_pk_fma_f32 v[52:53], v[102:103], v[118:119], v[54:55] op_sel_hi:[1,0,1]
	v_pk_mul_f32 v[0:1], v[52:53], v[120:121] op_sel_hi:[0,1]
	v_pk_fma_f32 v[0:1], v[52:53], v[122:123], v[0:1] op_sel:[1,0,0]
	v_pk_mul_f32 v[126:127], v[110:111], v[126:127] op_sel_hi:[0,1]
	ds_read_b128 v[120:123], v90 offset:0x4a00
	v_add_f32_dpp v0, v0, v0 quad_perm:[1,0,3,2] row_mask:0xf bank_mask:0xf bound_ctrl:1
	v_add_f32_dpp v1, v1, v1 quad_perm:[1,0,3,2] row_mask:0xf bank_mask:0xf bound_ctrl:1
	v_pk_fma_f32 v[54:55], v[52:53], v[124:125], v[126:127]
	v_add_f32_dpp v0, v0, v0 quad_perm:[2,3,0,1] row_mask:0xf bank_mask:0xf bound_ctrl:1
	ds_read_b128 v[124:127], v90 offset:0xa00
	s_nop 0
	v_add_f32_dpp v0, v0, v0 row_half_mirror row_mask:0xf bank_mask:0xf bound_ctrl:1
	ds_read2st64_b32 v[108:109], v89 offset0:196 offset1:197
	ds_read2st64_b64 v[100:103], v88 offset0:68 offset1:69
	v_add_f32_dpp v2, v0, v0 row_mirror row_mask:0xf bank_mask:0xf bound_ctrl:1
	v_add_f32_dpp v0, v0, v0 row_mirror row_mask:0xf bank_mask:0xf bound_ctrl:1
	s_nop 0
	s_waitcnt lgkmcnt(7)
	v_permlane16_swap_b32_e32 v0, v2
	v_add_f32_e32 v0, v0, v2
	v_pk_fma_f32 v[52:53], v[104:105], v[0:1], v[54:55] op_sel_hi:[1,0,1]
	v_pk_mul_f32 v[118:119], v[52:53], v[4:5] op_sel_hi:[0,1]
	v_pk_fma_f32 v[118:119], v[52:53], v[6:7], v[118:119] op_sel:[1,0,0]
	v_pk_mul_f32 v[10:11], v[110:111], v[10:11] op_sel:[1,0]
	ds_read_b128 v[4:7], v90 offset:0x4c00
	v_add_f32_dpp v118, v118, v118 quad_perm:[1,0,3,2] row_mask:0xf bank_mask:0xf bound_ctrl:1
	v_add_f32_dpp v119, v119, v119 quad_perm:[1,0,3,2] row_mask:0xf bank_mask:0xf bound_ctrl:1
	v_pk_fma_f32 v[54:55], v[52:53], v[8:9], v[10:11]
	v_add_f32_dpp v118, v118, v118 quad_perm:[2,3,0,1] row_mask:0xf bank_mask:0xf bound_ctrl:1
	ds_read_b128 v[8:11], v90 offset:0xc00
	s_nop 0
	v_add_f32_dpp v118, v118, v118 row_half_mirror row_mask:0xf bank_mask:0xf bound_ctrl:1
	ds_write2_b32 v93, v1, v119 offset0:72 offset1:108
	s_nop 0
	v_add_f32_dpp v2, v118, v118 row_mirror row_mask:0xf bank_mask:0xf bound_ctrl:1
	v_add_f32_dpp v118, v118, v118 row_mirror row_mask:0xf bank_mask:0xf bound_ctrl:1
	s_nop 0
	s_waitcnt lgkmcnt(4)
	v_permlane16_swap_b32_e32 v118, v2
	v_add_f32_e32 v118, v118, v2
	v_pk_fma_f32 v[52:53], v[106:107], v[118:119], v[54:55] op_sel_hi:[1,0,1]
	v_pk_mul_f32 v[0:1], v[52:53], v[112:113] op_sel_hi:[0,1]
	v_pk_fma_f32 v[0:1], v[52:53], v[114:115], v[0:1] op_sel:[1,0,0]
	v_pk_mul_f32 v[98:99], v[108:109], v[98:99] op_sel_hi:[0,1]
	ds_read_b128 v[112:115], v90 offset:0x4e00
	v_add_f32_dpp v0, v0, v0 quad_perm:[1,0,3,2] row_mask:0xf bank_mask:0xf bound_ctrl:1
	v_add_f32_dpp v1, v1, v1 quad_perm:[1,0,3,2] row_mask:0xf bank_mask:0xf bound_ctrl:1
	v_pk_fma_f32 v[54:55], v[52:53], v[96:97], v[98:99]
	v_add_f32_dpp v0, v0, v0 quad_perm:[2,3,0,1] row_mask:0xf bank_mask:0xf bound_ctrl:1
	ds_read_b128 v[96:99], v90 offset:0xe00
	s_nop 0
	v_add_f32_dpp v0, v0, v0 row_half_mirror row_mask:0xf bank_mask:0xf bound_ctrl:1
	ds_read2st64_b32 v[110:111], v89 offset0:198 offset1:199
	ds_read2st64_b64 v[104:107], v88 offset0:70 offset1:71
	v_add_f32_dpp v2, v0, v0 row_mirror row_mask:0xf bank_mask:0xf bound_ctrl:1
	v_add_f32_dpp v0, v0, v0 row_mirror row_mask:0xf bank_mask:0xf bound_ctrl:1
	s_nop 0
	s_waitcnt lgkmcnt(7)
	v_permlane16_swap_b32_e32 v0, v2
	v_add_f32_e32 v0, v0, v2
	v_pk_fma_f32 v[52:53], v[100:101], v[0:1], v[54:55] op_sel_hi:[1,0,1]
	v_pk_mul_f32 v[118:119], v[52:53], v[120:121] op_sel_hi:[0,1]
	v_pk_fma_f32 v[118:119], v[52:53], v[122:123], v[118:119] op_sel:[1,0,0]
	v_pk_mul_f32 v[126:127], v[108:109], v[126:127] op_sel:[1,0]
	ds_read_b128 v[120:123], v90 offset:0x5000
	v_add_f32_dpp v118, v118, v118 quad_perm:[1,0,3,2] row_mask:0xf bank_mask:0xf bound_ctrl:1
	v_add_f32_dpp v119, v119, v119 quad_perm:[1,0,3,2] row_mask:0xf bank_mask:0xf bound_ctrl:1
	v_pk_fma_f32 v[54:55], v[52:53], v[124:125], v[126:127]
	v_add_f32_dpp v118, v118, v118 quad_perm:[2,3,0,1] row_mask:0xf bank_mask:0xf bound_ctrl:1
	ds_read_b128 v[124:127], v90 offset:0x1000
	s_nop 0
	v_add_f32_dpp v118, v118, v118 row_half_mirror row_mask:0xf bank_mask:0xf bound_ctrl:1
	ds_write2_b32 v93, v1, v119 offset0:144 offset1:180
	s_nop 0
	v_add_f32_dpp v2, v118, v118 row_mirror row_mask:0xf bank_mask:0xf bound_ctrl:1
	v_add_f32_dpp v118, v118, v118 row_mirror row_mask:0xf bank_mask:0xf bound_ctrl:1
	s_nop 0
	s_waitcnt lgkmcnt(4)
	v_permlane16_swap_b32_e32 v118, v2
	v_add_f32_e32 v118, v118, v2
	v_pk_fma_f32 v[52:53], v[102:103], v[118:119], v[54:55] op_sel_hi:[1,0,1]
	v_pk_mul_f32 v[0:1], v[52:53], v[4:5] op_sel_hi:[0,1]
	v_pk_fma_f32 v[0:1], v[52:53], v[6:7], v[0:1] op_sel:[1,0,0]
	v_pk_mul_f32 v[10:11], v[110:111], v[10:11] op_sel_hi:[0,1]
	ds_read_b128 v[4:7], v90 offset:0x5200
	v_add_f32_dpp v0, v0, v0 quad_perm:[1,0,3,2] row_mask:0xf bank_mask:0xf bound_ctrl:1
	v_add_f32_dpp v1, v1, v1 quad_perm:[1,0,3,2] row_mask:0xf bank_mask:0xf bound_ctrl:1
	v_pk_fma_f32 v[54:55], v[52:53], v[8:9], v[10:11]
	v_add_f32_dpp v0, v0, v0 quad_perm:[2,3,0,1] row_mask:0xf bank_mask:0xf bound_ctrl:1
	ds_read_b128 v[8:11], v90 offset:0x1200
	s_nop 0
	v_add_f32_dpp v0, v0, v0 row_half_mirror row_mask:0xf bank_mask:0xf bound_ctrl:1
	ds_read2st64_b32 v[108:109], v89 offset0:200 offset1:201
	ds_read2st64_b64 v[100:103], v88 offset0:72 offset1:73
	v_add_f32_dpp v2, v0, v0 row_mirror row_mask:0xf bank_mask:0xf bound_ctrl:1
	v_add_f32_dpp v0, v0, v0 row_mirror row_mask:0xf bank_mask:0xf bound_ctrl:1
	s_nop 0
	s_waitcnt lgkmcnt(7)
	v_permlane16_swap_b32_e32 v0, v2
	v_add_f32_e32 v0, v0, v2
	v_pk_fma_f32 v[52:53], v[104:105], v[0:1], v[54:55] op_sel_hi:[1,0,1]
	v_pk_mul_f32 v[118:119], v[52:53], v[112:113] op_sel_hi:[0,1]
	v_pk_fma_f32 v[118:119], v[52:53], v[114:115], v[118:119] op_sel:[1,0,0]
	v_pk_mul_f32 v[98:99], v[110:111], v[98:99] op_sel:[1,0]
	ds_read_b128 v[112:115], v90 offset:0x5400
	v_add_f32_dpp v118, v118, v118 quad_perm:[1,0,3,2] row_mask:0xf bank_mask:0xf bound_ctrl:1
	v_add_f32_dpp v119, v119, v119 quad_perm:[1,0,3,2] row_mask:0xf bank_mask:0xf bound_ctrl:1
	v_pk_fma_f32 v[54:55], v[52:53], v[96:97], v[98:99]
	v_add_f32_dpp v118, v118, v118 quad_perm:[2,3,0,1] row_mask:0xf bank_mask:0xf bound_ctrl:1
	ds_read_b128 v[96:99], v90 offset:0x1400
	s_nop 0
	v_add_f32_dpp v118, v118, v118 row_half_mirror row_mask:0xf bank_mask:0xf bound_ctrl:1
	ds_write2_b32 v93, v1, v119 offset0:216 offset1:252
	s_nop 0
	v_add_f32_dpp v2, v118, v118 row_mirror row_mask:0xf bank_mask:0xf bound_ctrl:1
	v_add_f32_dpp v118, v118, v118 row_mirror row_mask:0xf bank_mask:0xf bound_ctrl:1
	s_nop 0
	s_waitcnt lgkmcnt(4)
	v_permlane16_swap_b32_e32 v118, v2
	v_add_f32_e32 v118, v118, v2
	v_pk_fma_f32 v[52:53], v[106:107], v[118:119], v[54:55] op_sel_hi:[1,0,1]
	v_pk_mul_f32 v[0:1], v[52:53], v[120:121] op_sel_hi:[0,1]
	v_pk_fma_f32 v[0:1], v[52:53], v[122:123], v[0:1] op_sel:[1,0,0]
	v_pk_mul_f32 v[126:127], v[108:109], v[126:127] op_sel_hi:[0,1]
	ds_read_b128 v[120:123], v90 offset:0x5600
	v_add_f32_dpp v0, v0, v0 quad_perm:[1,0,3,2] row_mask:0xf bank_mask:0xf bound_ctrl:1
	v_add_f32_dpp v1, v1, v1 quad_perm:[1,0,3,2] row_mask:0xf bank_mask:0xf bound_ctrl:1
	v_pk_fma_f32 v[54:55], v[52:53], v[124:125], v[126:127]
	v_add_f32_dpp v0, v0, v0 quad_perm:[2,3,0,1] row_mask:0xf bank_mask:0xf bound_ctrl:1
	ds_read_b128 v[124:127], v90 offset:0x1600
	s_nop 0
	v_add_f32_dpp v0, v0, v0 row_half_mirror row_mask:0xf bank_mask:0xf bound_ctrl:1
	ds_read2st64_b32 v[110:111], v89 offset0:202 offset1:203
	ds_read2st64_b64 v[104:107], v88 offset0:74 offset1:75
	v_add_f32_dpp v2, v0, v0 row_mirror row_mask:0xf bank_mask:0xf bound_ctrl:1
	v_add_f32_dpp v0, v0, v0 row_mirror row_mask:0xf bank_mask:0xf bound_ctrl:1
	v_add_u32_e32 v93, 0x480, v93
	s_waitcnt lgkmcnt(7)
	v_permlane16_swap_b32_e32 v0, v2
	v_add_f32_e32 v0, v0, v2
	v_pk_fma_f32 v[52:53], v[100:101], v[0:1], v[54:55] op_sel_hi:[1,0,1]
	v_pk_mul_f32 v[118:119], v[52:53], v[4:5] op_sel_hi:[0,1]
	v_pk_fma_f32 v[118:119], v[52:53], v[6:7], v[118:119] op_sel:[1,0,0]
	v_pk_mul_f32 v[10:11], v[108:109], v[10:11] op_sel:[1,0]
	ds_read_b128 v[4:7], v90 offset:0x5800
	v_add_f32_dpp v118, v118, v118 quad_perm:[1,0,3,2] row_mask:0xf bank_mask:0xf bound_ctrl:1
	v_add_f32_dpp v119, v119, v119 quad_perm:[1,0,3,2] row_mask:0xf bank_mask:0xf bound_ctrl:1
	v_pk_fma_f32 v[54:55], v[52:53], v[8:9], v[10:11]
	v_add_f32_dpp v118, v118, v118 quad_perm:[2,3,0,1] row_mask:0xf bank_mask:0xf bound_ctrl:1
	ds_read_b128 v[8:11], v90 offset:0x1800
	s_nop 0
	v_add_f32_dpp v118, v118, v118 row_half_mirror row_mask:0xf bank_mask:0xf bound_ctrl:1
	ds_write2_b32 v93, v1, v119 offset0:0 offset1:36
	s_nop 0
	v_add_f32_dpp v2, v118, v118 row_mirror row_mask:0xf bank_mask:0xf bound_ctrl:1
	v_add_f32_dpp v118, v118, v118 row_mirror row_mask:0xf bank_mask:0xf bound_ctrl:1
	s_nop 0
	s_waitcnt lgkmcnt(4)
	v_permlane16_swap_b32_e32 v118, v2
	v_add_f32_e32 v118, v118, v2
	v_pk_fma_f32 v[52:53], v[102:103], v[118:119], v[54:55] op_sel_hi:[1,0,1]
	v_pk_mul_f32 v[0:1], v[52:53], v[112:113] op_sel_hi:[0,1]
	v_pk_fma_f32 v[0:1], v[52:53], v[114:115], v[0:1] op_sel:[1,0,0]
	v_pk_mul_f32 v[98:99], v[110:111], v[98:99] op_sel_hi:[0,1]
	ds_read_b128 v[112:115], v90 offset:0x5a00
	v_add_f32_dpp v0, v0, v0 quad_perm:[1,0,3,2] row_mask:0xf bank_mask:0xf bound_ctrl:1
	v_add_f32_dpp v1, v1, v1 quad_perm:[1,0,3,2] row_mask:0xf bank_mask:0xf bound_ctrl:1
	v_pk_fma_f32 v[54:55], v[52:53], v[96:97], v[98:99]
	v_add_f32_dpp v0, v0, v0 quad_perm:[2,3,0,1] row_mask:0xf bank_mask:0xf bound_ctrl:1
	ds_read_b128 v[96:99], v90 offset:0x1a00
	s_nop 0
	v_add_f32_dpp v0, v0, v0 row_half_mirror row_mask:0xf bank_mask:0xf bound_ctrl:1
	ds_read2st64_b32 v[108:109], v89 offset0:204 offset1:205
	ds_read2st64_b64 v[100:103], v88 offset0:76 offset1:77
	v_add_f32_dpp v2, v0, v0 row_mirror row_mask:0xf bank_mask:0xf bound_ctrl:1
	v_add_f32_dpp v0, v0, v0 row_mirror row_mask:0xf bank_mask:0xf bound_ctrl:1
	s_nop 0
	s_waitcnt lgkmcnt(7)
	v_permlane16_swap_b32_e32 v0, v2
	v_add_f32_e32 v0, v0, v2
	v_pk_fma_f32 v[52:53], v[104:105], v[0:1], v[54:55] op_sel_hi:[1,0,1]
	v_pk_mul_f32 v[118:119], v[52:53], v[120:121] op_sel_hi:[0,1]
	v_pk_fma_f32 v[118:119], v[52:53], v[122:123], v[118:119] op_sel:[1,0,0]
	v_pk_mul_f32 v[126:127], v[110:111], v[126:127] op_sel:[1,0]
	ds_read_b128 v[120:123], v90 offset:0x5c00
	v_add_f32_dpp v118, v118, v118 quad_perm:[1,0,3,2] row_mask:0xf bank_mask:0xf bound_ctrl:1
	v_add_f32_dpp v119, v119, v119 quad_perm:[1,0,3,2] row_mask:0xf bank_mask:0xf bound_ctrl:1
	v_pk_fma_f32 v[54:55], v[52:53], v[124:125], v[126:127]
	v_add_f32_dpp v118, v118, v118 quad_perm:[2,3,0,1] row_mask:0xf bank_mask:0xf bound_ctrl:1
	ds_read_b128 v[124:127], v90 offset:0x1c00
	s_nop 0
	v_add_f32_dpp v118, v118, v118 row_half_mirror row_mask:0xf bank_mask:0xf bound_ctrl:1
	ds_write2_b32 v93, v1, v119 offset0:72 offset1:108
	s_nop 0
	v_add_f32_dpp v2, v118, v118 row_mirror row_mask:0xf bank_mask:0xf bound_ctrl:1
	v_add_f32_dpp v118, v118, v118 row_mirror row_mask:0xf bank_mask:0xf bound_ctrl:1
	s_nop 0
	s_waitcnt lgkmcnt(4)
	v_permlane16_swap_b32_e32 v118, v2
	v_add_f32_e32 v118, v118, v2
	v_pk_fma_f32 v[52:53], v[106:107], v[118:119], v[54:55] op_sel_hi:[1,0,1]
	v_pk_mul_f32 v[0:1], v[52:53], v[4:5] op_sel_hi:[0,1]
	v_pk_fma_f32 v[0:1], v[52:53], v[6:7], v[0:1] op_sel:[1,0,0]
	v_pk_mul_f32 v[10:11], v[108:109], v[10:11] op_sel_hi:[0,1]
	ds_read_b128 v[4:7], v90 offset:0x5e00
	v_add_f32_dpp v0, v0, v0 quad_perm:[1,0,3,2] row_mask:0xf bank_mask:0xf bound_ctrl:1
	v_add_f32_dpp v1, v1, v1 quad_perm:[1,0,3,2] row_mask:0xf bank_mask:0xf bound_ctrl:1
	v_pk_fma_f32 v[54:55], v[52:53], v[8:9], v[10:11]
	v_add_f32_dpp v0, v0, v0 quad_perm:[2,3,0,1] row_mask:0xf bank_mask:0xf bound_ctrl:1
	ds_read_b128 v[8:11], v90 offset:0x1e00
	s_nop 0
	v_add_f32_dpp v0, v0, v0 row_half_mirror row_mask:0xf bank_mask:0xf bound_ctrl:1
	ds_read2st64_b32 v[110:111], v89 offset0:206 offset1:207
	ds_read2st64_b64 v[104:107], v88 offset0:78 offset1:79
	v_add_f32_dpp v2, v0, v0 row_mirror row_mask:0xf bank_mask:0xf bound_ctrl:1
	v_add_f32_dpp v0, v0, v0 row_mirror row_mask:0xf bank_mask:0xf bound_ctrl:1
	s_nop 0
	s_waitcnt lgkmcnt(7)
	v_permlane16_swap_b32_e32 v0, v2
	v_add_f32_e32 v0, v0, v2
	v_pk_fma_f32 v[52:53], v[100:101], v[0:1], v[54:55] op_sel_hi:[1,0,1]
	v_pk_mul_f32 v[118:119], v[52:53], v[112:113] op_sel_hi:[0,1]
	v_pk_fma_f32 v[118:119], v[52:53], v[114:115], v[118:119] op_sel:[1,0,0]
	v_pk_mul_f32 v[98:99], v[108:109], v[98:99] op_sel:[1,0]
	ds_read_b128 v[112:115], v90 offset:0x6000
	v_add_f32_dpp v118, v118, v118 quad_perm:[1,0,3,2] row_mask:0xf bank_mask:0xf bound_ctrl:1
	v_add_f32_dpp v119, v119, v119 quad_perm:[1,0,3,2] row_mask:0xf bank_mask:0xf bound_ctrl:1
	v_pk_fma_f32 v[54:55], v[52:53], v[96:97], v[98:99]
	v_add_f32_dpp v118, v118, v118 quad_perm:[2,3,0,1] row_mask:0xf bank_mask:0xf bound_ctrl:1
	ds_read_b128 v[96:99], v90 offset:0x2000
	s_nop 0
	v_add_f32_dpp v118, v118, v118 row_half_mirror row_mask:0xf bank_mask:0xf bound_ctrl:1
	ds_write2_b32 v93, v1, v119 offset0:144 offset1:180
	s_nop 0
	v_add_f32_dpp v2, v118, v118 row_mirror row_mask:0xf bank_mask:0xf bound_ctrl:1
	v_add_f32_dpp v118, v118, v118 row_mirror row_mask:0xf bank_mask:0xf bound_ctrl:1
	s_nop 0
	s_waitcnt lgkmcnt(4)
	v_permlane16_swap_b32_e32 v118, v2
	v_add_f32_e32 v118, v118, v2
	v_pk_fma_f32 v[52:53], v[102:103], v[118:119], v[54:55] op_sel_hi:[1,0,1]
	v_pk_mul_f32 v[0:1], v[52:53], v[120:121] op_sel_hi:[0,1]
	v_pk_fma_f32 v[0:1], v[52:53], v[122:123], v[0:1] op_sel:[1,0,0]
	v_pk_mul_f32 v[126:127], v[110:111], v[126:127] op_sel_hi:[0,1]
	ds_read_b128 v[120:123], v90 offset:0x6200
	v_add_f32_dpp v0, v0, v0 quad_perm:[1,0,3,2] row_mask:0xf bank_mask:0xf bound_ctrl:1
	v_add_f32_dpp v1, v1, v1 quad_perm:[1,0,3,2] row_mask:0xf bank_mask:0xf bound_ctrl:1
	v_pk_fma_f32 v[54:55], v[52:53], v[124:125], v[126:127]
	v_add_f32_dpp v0, v0, v0 quad_perm:[2,3,0,1] row_mask:0xf bank_mask:0xf bound_ctrl:1
	ds_read_b128 v[124:127], v90 offset:0x2200
	s_nop 0
	v_add_f32_dpp v0, v0, v0 row_half_mirror row_mask:0xf bank_mask:0xf bound_ctrl:1
	ds_read2st64_b32 v[108:109], v89 offset0:208 offset1:209
	ds_read2st64_b64 v[100:103], v88 offset0:80 offset1:81
	v_add_f32_dpp v2, v0, v0 row_mirror row_mask:0xf bank_mask:0xf bound_ctrl:1
	v_add_f32_dpp v0, v0, v0 row_mirror row_mask:0xf bank_mask:0xf bound_ctrl:1
	s_nop 0
	s_waitcnt lgkmcnt(7)
	v_permlane16_swap_b32_e32 v0, v2
	v_add_f32_e32 v0, v0, v2
	v_pk_fma_f32 v[52:53], v[104:105], v[0:1], v[54:55] op_sel_hi:[1,0,1]
	v_pk_mul_f32 v[118:119], v[52:53], v[4:5] op_sel_hi:[0,1]
	v_pk_fma_f32 v[118:119], v[52:53], v[6:7], v[118:119] op_sel:[1,0,0]
	v_pk_mul_f32 v[10:11], v[110:111], v[10:11] op_sel:[1,0]
	ds_read_b128 v[4:7], v90 offset:0x6400
	v_add_f32_dpp v118, v118, v118 quad_perm:[1,0,3,2] row_mask:0xf bank_mask:0xf bound_ctrl:1
	v_add_f32_dpp v119, v119, v119 quad_perm:[1,0,3,2] row_mask:0xf bank_mask:0xf bound_ctrl:1
	v_pk_fma_f32 v[54:55], v[52:53], v[8:9], v[10:11]
	v_add_f32_dpp v118, v118, v118 quad_perm:[2,3,0,1] row_mask:0xf bank_mask:0xf bound_ctrl:1
	ds_read_b128 v[8:11], v90 offset:0x2400
	s_nop 0
	v_add_f32_dpp v118, v118, v118 row_half_mirror row_mask:0xf bank_mask:0xf bound_ctrl:1
	ds_write2_b32 v93, v1, v119 offset0:216 offset1:252
	s_nop 0
	v_add_f32_dpp v2, v118, v118 row_mirror row_mask:0xf bank_mask:0xf bound_ctrl:1
	v_add_f32_dpp v118, v118, v118 row_mirror row_mask:0xf bank_mask:0xf bound_ctrl:1
	s_nop 0
	s_waitcnt lgkmcnt(4)
	v_permlane16_swap_b32_e32 v118, v2
	v_add_f32_e32 v118, v118, v2
	v_pk_fma_f32 v[52:53], v[106:107], v[118:119], v[54:55] op_sel_hi:[1,0,1]
	s_cmp_eq_u32 s88, 0x800000
	s_cbranch_scc1 .LBB0_684
	v_pk_mul_f32 v[0:1], v[52:53], v[112:113] op_sel_hi:[0,1]
	v_pk_fma_f32 v[0:1], v[52:53], v[114:115], v[0:1] op_sel:[1,0,0]
	v_pk_mul_f32 v[98:99], v[108:109], v[98:99] op_sel_hi:[0,1]
	ds_read_b128 v[112:115], v90 offset:0x6600
	v_add_f32_dpp v0, v0, v0 quad_perm:[1,0,3,2] row_mask:0xf bank_mask:0xf bound_ctrl:1
	v_add_f32_dpp v1, v1, v1 quad_perm:[1,0,3,2] row_mask:0xf bank_mask:0xf bound_ctrl:1
	v_pk_fma_f32 v[54:55], v[52:53], v[96:97], v[98:99]
	v_add_f32_dpp v0, v0, v0 quad_perm:[2,3,0,1] row_mask:0xf bank_mask:0xf bound_ctrl:1
	ds_read_b128 v[96:99], v90 offset:0x2600
	s_nop 0
	v_add_f32_dpp v0, v0, v0 row_half_mirror row_mask:0xf bank_mask:0xf bound_ctrl:1
	ds_read2st64_b32 v[110:111], v89 offset0:210 offset1:211
	ds_read2st64_b64 v[104:107], v88 offset0:82 offset1:83
	v_add_f32_dpp v2, v0, v0 row_mirror row_mask:0xf bank_mask:0xf bound_ctrl:1
	v_add_f32_dpp v0, v0, v0 row_mirror row_mask:0xf bank_mask:0xf bound_ctrl:1
	v_add_u32_e32 v93, 0x480, v93
	s_waitcnt lgkmcnt(7)
	v_permlane16_swap_b32_e32 v0, v2
	v_add_f32_e32 v0, v0, v2
	v_pk_fma_f32 v[52:53], v[100:101], v[0:1], v[54:55] op_sel_hi:[1,0,1]
	v_pk_mul_f32 v[118:119], v[52:53], v[120:121] op_sel_hi:[0,1]
	v_pk_fma_f32 v[118:119], v[52:53], v[122:123], v[118:119] op_sel:[1,0,0]
	v_pk_mul_f32 v[126:127], v[108:109], v[126:127] op_sel:[1,0]
	ds_read_b128 v[120:123], v90 offset:0x6800
	v_add_f32_dpp v118, v118, v118 quad_perm:[1,0,3,2] row_mask:0xf bank_mask:0xf bound_ctrl:1
	v_add_f32_dpp v119, v119, v119 quad_perm:[1,0,3,2] row_mask:0xf bank_mask:0xf bound_ctrl:1
	v_pk_fma_f32 v[54:55], v[52:53], v[124:125], v[126:127]
	v_add_f32_dpp v118, v118, v118 quad_perm:[2,3,0,1] row_mask:0xf bank_mask:0xf bound_ctrl:1
	ds_read_b128 v[124:127], v90 offset:0x2800
	s_nop 0
	v_add_f32_dpp v118, v118, v118 row_half_mirror row_mask:0xf bank_mask:0xf bound_ctrl:1
	ds_write2_b32 v93, v1, v119 offset0:0 offset1:36
	s_nop 0
	v_add_f32_dpp v2, v118, v118 row_mirror row_mask:0xf bank_mask:0xf bound_ctrl:1
	v_add_f32_dpp v118, v118, v118 row_mirror row_mask:0xf bank_mask:0xf bound_ctrl:1
	s_nop 0
	s_waitcnt lgkmcnt(4)
	v_permlane16_swap_b32_e32 v118, v2
	v_add_f32_e32 v118, v118, v2
	v_pk_fma_f32 v[52:53], v[102:103], v[118:119], v[54:55] op_sel_hi:[1,0,1]
	v_pk_mul_f32 v[0:1], v[52:53], v[4:5] op_sel_hi:[0,1]
	v_pk_fma_f32 v[0:1], v[52:53], v[6:7], v[0:1] op_sel:[1,0,0]
	v_pk_mul_f32 v[10:11], v[110:111], v[10:11] op_sel_hi:[0,1]
	ds_read_b128 v[4:7], v90 offset:0x6a00
	v_add_f32_dpp v0, v0, v0 quad_perm:[1,0,3,2] row_mask:0xf bank_mask:0xf bound_ctrl:1
	v_add_f32_dpp v1, v1, v1 quad_perm:[1,0,3,2] row_mask:0xf bank_mask:0xf bound_ctrl:1
	v_pk_fma_f32 v[54:55], v[52:53], v[8:9], v[10:11]
	v_add_f32_dpp v0, v0, v0 quad_perm:[2,3,0,1] row_mask:0xf bank_mask:0xf bound_ctrl:1
	ds_read_b128 v[8:11], v90 offset:0x2a00
	s_nop 0
	v_add_f32_dpp v0, v0, v0 row_half_mirror row_mask:0xf bank_mask:0xf bound_ctrl:1
	ds_read2st64_b32 v[108:109], v89 offset0:212 offset1:213
	ds_read2st64_b64 v[100:103], v88 offset0:84 offset1:85
	v_add_f32_dpp v2, v0, v0 row_mirror row_mask:0xf bank_mask:0xf bound_ctrl:1
	v_add_f32_dpp v0, v0, v0 row_mirror row_mask:0xf bank_mask:0xf bound_ctrl:1
	s_nop 0
	s_waitcnt lgkmcnt(7)
	v_permlane16_swap_b32_e32 v0, v2
	v_add_f32_e32 v0, v0, v2
	v_pk_fma_f32 v[52:53], v[104:105], v[0:1], v[54:55] op_sel_hi:[1,0,1]
	v_pk_mul_f32 v[118:119], v[52:53], v[112:113] op_sel_hi:[0,1]
	v_pk_fma_f32 v[118:119], v[52:53], v[114:115], v[118:119] op_sel:[1,0,0]
	v_pk_mul_f32 v[98:99], v[110:111], v[98:99] op_sel:[1,0]
	ds_read_b128 v[112:115], v90 offset:0x6c00
	v_add_f32_dpp v118, v118, v118 quad_perm:[1,0,3,2] row_mask:0xf bank_mask:0xf bound_ctrl:1
	v_add_f32_dpp v119, v119, v119 quad_perm:[1,0,3,2] row_mask:0xf bank_mask:0xf bound_ctrl:1
	v_pk_fma_f32 v[54:55], v[52:53], v[96:97], v[98:99]
	v_add_f32_dpp v118, v118, v118 quad_perm:[2,3,0,1] row_mask:0xf bank_mask:0xf bound_ctrl:1
	ds_read_b128 v[96:99], v90 offset:0x2c00
	s_nop 0
	v_add_f32_dpp v118, v118, v118 row_half_mirror row_mask:0xf bank_mask:0xf bound_ctrl:1
	ds_write2_b32 v93, v1, v119 offset0:72 offset1:108
	s_nop 0
	v_add_f32_dpp v2, v118, v118 row_mirror row_mask:0xf bank_mask:0xf bound_ctrl:1
	v_add_f32_dpp v118, v118, v118 row_mirror row_mask:0xf bank_mask:0xf bound_ctrl:1
	s_nop 0
	s_waitcnt lgkmcnt(4)
	v_permlane16_swap_b32_e32 v118, v2
	v_add_f32_e32 v118, v118, v2
	v_pk_fma_f32 v[52:53], v[106:107], v[118:119], v[54:55] op_sel_hi:[1,0,1]
	v_pk_mul_f32 v[0:1], v[52:53], v[120:121] op_sel_hi:[0,1]
	v_pk_fma_f32 v[0:1], v[52:53], v[122:123], v[0:1] op_sel:[1,0,0]
	v_pk_mul_f32 v[126:127], v[108:109], v[126:127] op_sel_hi:[0,1]
	ds_read_b128 v[120:123], v90 offset:0x6e00
	v_add_f32_dpp v0, v0, v0 quad_perm:[1,0,3,2] row_mask:0xf bank_mask:0xf bound_ctrl:1
	v_add_f32_dpp v1, v1, v1 quad_perm:[1,0,3,2] row_mask:0xf bank_mask:0xf bound_ctrl:1
	v_pk_fma_f32 v[54:55], v[52:53], v[124:125], v[126:127]
	v_add_f32_dpp v0, v0, v0 quad_perm:[2,3,0,1] row_mask:0xf bank_mask:0xf bound_ctrl:1
	ds_read_b128 v[124:127], v90 offset:0x2e00
	s_nop 0
	v_add_f32_dpp v0, v0, v0 row_half_mirror row_mask:0xf bank_mask:0xf bound_ctrl:1
	ds_read2st64_b32 v[110:111], v89 offset0:214 offset1:215
	ds_read2st64_b64 v[104:107], v88 offset0:86 offset1:87
	v_add_f32_dpp v2, v0, v0 row_mirror row_mask:0xf bank_mask:0xf bound_ctrl:1
	v_add_f32_dpp v0, v0, v0 row_mirror row_mask:0xf bank_mask:0xf bound_ctrl:1
	s_nop 0
	s_waitcnt lgkmcnt(7)
	v_permlane16_swap_b32_e32 v0, v2
	v_add_f32_e32 v0, v0, v2
	v_pk_fma_f32 v[52:53], v[100:101], v[0:1], v[54:55] op_sel_hi:[1,0,1]
	v_pk_mul_f32 v[118:119], v[52:53], v[4:5] op_sel_hi:[0,1]
	v_pk_fma_f32 v[118:119], v[52:53], v[6:7], v[118:119] op_sel:[1,0,0]
	v_pk_mul_f32 v[10:11], v[108:109], v[10:11] op_sel:[1,0]
	ds_read_b128 v[4:7], v90 offset:0x7000
	v_add_f32_dpp v118, v118, v118 quad_perm:[1,0,3,2] row_mask:0xf bank_mask:0xf bound_ctrl:1
	v_add_f32_dpp v119, v119, v119 quad_perm:[1,0,3,2] row_mask:0xf bank_mask:0xf bound_ctrl:1
	v_pk_fma_f32 v[54:55], v[52:53], v[8:9], v[10:11]
	v_add_f32_dpp v118, v118, v118 quad_perm:[2,3,0,1] row_mask:0xf bank_mask:0xf bound_ctrl:1
	ds_read_b128 v[8:11], v90 offset:0x3000
	s_nop 0
	v_add_f32_dpp v118, v118, v118 row_half_mirror row_mask:0xf bank_mask:0xf bound_ctrl:1
	ds_write2_b32 v93, v1, v119 offset0:144 offset1:180
	s_nop 0
	v_add_f32_dpp v2, v118, v118 row_mirror row_mask:0xf bank_mask:0xf bound_ctrl:1
	v_add_f32_dpp v118, v118, v118 row_mirror row_mask:0xf bank_mask:0xf bound_ctrl:1
	s_nop 0
	s_waitcnt lgkmcnt(4)
	v_permlane16_swap_b32_e32 v118, v2
	v_add_f32_e32 v118, v118, v2
	v_pk_fma_f32 v[52:53], v[102:103], v[118:119], v[54:55] op_sel_hi:[1,0,1]
	v_pk_mul_f32 v[0:1], v[52:53], v[112:113] op_sel_hi:[0,1]
	v_pk_fma_f32 v[0:1], v[52:53], v[114:115], v[0:1] op_sel:[1,0,0]
	v_pk_mul_f32 v[98:99], v[110:111], v[98:99] op_sel_hi:[0,1]
	ds_read_b128 v[112:115], v90 offset:0x7200
	v_add_f32_dpp v0, v0, v0 quad_perm:[1,0,3,2] row_mask:0xf bank_mask:0xf bound_ctrl:1
	v_add_f32_dpp v1, v1, v1 quad_perm:[1,0,3,2] row_mask:0xf bank_mask:0xf bound_ctrl:1
	v_pk_fma_f32 v[54:55], v[52:53], v[96:97], v[98:99]
	v_add_f32_dpp v0, v0, v0 quad_perm:[2,3,0,1] row_mask:0xf bank_mask:0xf bound_ctrl:1
	ds_read_b128 v[96:99], v90 offset:0x3200
	s_nop 0
	v_add_f32_dpp v0, v0, v0 row_half_mirror row_mask:0xf bank_mask:0xf bound_ctrl:1
	ds_read2st64_b32 v[108:109], v89 offset0:216 offset1:217
	ds_read2st64_b64 v[100:103], v88 offset0:88 offset1:89
	v_add_f32_dpp v2, v0, v0 row_mirror row_mask:0xf bank_mask:0xf bound_ctrl:1
	v_add_f32_dpp v0, v0, v0 row_mirror row_mask:0xf bank_mask:0xf bound_ctrl:1
	s_nop 0
	s_waitcnt lgkmcnt(7)
	v_permlane16_swap_b32_e32 v0, v2
	v_add_f32_e32 v0, v0, v2
	v_pk_fma_f32 v[52:53], v[104:105], v[0:1], v[54:55] op_sel_hi:[1,0,1]
	v_pk_mul_f32 v[118:119], v[52:53], v[120:121] op_sel_hi:[0,1]
	v_pk_fma_f32 v[118:119], v[52:53], v[122:123], v[118:119] op_sel:[1,0,0]
	v_pk_mul_f32 v[126:127], v[110:111], v[126:127] op_sel:[1,0]
	ds_read_b128 v[120:123], v90 offset:0x7400
	v_add_f32_dpp v118, v118, v118 quad_perm:[1,0,3,2] row_mask:0xf bank_mask:0xf bound_ctrl:1
	v_add_f32_dpp v119, v119, v119 quad_perm:[1,0,3,2] row_mask:0xf bank_mask:0xf bound_ctrl:1
	v_pk_fma_f32 v[54:55], v[52:53], v[124:125], v[126:127]
	v_add_f32_dpp v118, v118, v118 quad_perm:[2,3,0,1] row_mask:0xf bank_mask:0xf bound_ctrl:1
	ds_read_b128 v[124:127], v90 offset:0x3400
	s_nop 0
	v_add_f32_dpp v118, v118, v118 row_half_mirror row_mask:0xf bank_mask:0xf bound_ctrl:1
	ds_write2_b32 v93, v1, v119 offset0:216 offset1:252
	s_nop 0
	v_add_f32_dpp v2, v118, v118 row_mirror row_mask:0xf bank_mask:0xf bound_ctrl:1
	v_add_f32_dpp v118, v118, v118 row_mirror row_mask:0xf bank_mask:0xf bound_ctrl:1
	s_nop 0
	s_waitcnt lgkmcnt(4)
	v_permlane16_swap_b32_e32 v118, v2
	v_add_f32_e32 v118, v118, v2
	v_pk_fma_f32 v[52:53], v[106:107], v[118:119], v[54:55] op_sel_hi:[1,0,1]
	v_pk_mul_f32 v[0:1], v[52:53], v[4:5] op_sel_hi:[0,1]
	v_pk_fma_f32 v[0:1], v[52:53], v[6:7], v[0:1] op_sel:[1,0,0]
	v_pk_mul_f32 v[10:11], v[108:109], v[10:11] op_sel_hi:[0,1]
	ds_read_b128 v[4:7], v90 offset:0x7600
	v_add_f32_dpp v0, v0, v0 quad_perm:[1,0,3,2] row_mask:0xf bank_mask:0xf bound_ctrl:1
	v_add_f32_dpp v1, v1, v1 quad_perm:[1,0,3,2] row_mask:0xf bank_mask:0xf bound_ctrl:1
	v_pk_fma_f32 v[54:55], v[52:53], v[8:9], v[10:11]
	v_add_f32_dpp v0, v0, v0 quad_perm:[2,3,0,1] row_mask:0xf bank_mask:0xf bound_ctrl:1
	ds_read_b128 v[8:11], v90 offset:0x3600
	s_nop 0
	v_add_f32_dpp v0, v0, v0 row_half_mirror row_mask:0xf bank_mask:0xf bound_ctrl:1
	ds_read2st64_b32 v[110:111], v89 offset0:218 offset1:219
	ds_read2st64_b64 v[104:107], v88 offset0:90 offset1:91
	v_add_f32_dpp v2, v0, v0 row_mirror row_mask:0xf bank_mask:0xf bound_ctrl:1
	v_add_f32_dpp v0, v0, v0 row_mirror row_mask:0xf bank_mask:0xf bound_ctrl:1
	v_add_u32_e32 v93, 0x480, v93
	s_waitcnt lgkmcnt(7)
	v_permlane16_swap_b32_e32 v0, v2
	v_add_f32_e32 v0, v0, v2
	v_pk_fma_f32 v[52:53], v[100:101], v[0:1], v[54:55] op_sel_hi:[1,0,1]
	v_pk_mul_f32 v[118:119], v[52:53], v[112:113] op_sel_hi:[0,1]
	v_pk_fma_f32 v[118:119], v[52:53], v[114:115], v[118:119] op_sel:[1,0,0]
	v_pk_mul_f32 v[98:99], v[108:109], v[98:99] op_sel:[1,0]
	ds_read_b128 v[112:115], v90 offset:0x7800
	v_add_f32_dpp v118, v118, v118 quad_perm:[1,0,3,2] row_mask:0xf bank_mask:0xf bound_ctrl:1
	v_add_f32_dpp v119, v119, v119 quad_perm:[1,0,3,2] row_mask:0xf bank_mask:0xf bound_ctrl:1
	v_pk_fma_f32 v[54:55], v[52:53], v[96:97], v[98:99]
	v_add_f32_dpp v118, v118, v118 quad_perm:[2,3,0,1] row_mask:0xf bank_mask:0xf bound_ctrl:1
	ds_read_b128 v[96:99], v90 offset:0x3800
	s_nop 0
	v_add_f32_dpp v118, v118, v118 row_half_mirror row_mask:0xf bank_mask:0xf bound_ctrl:1
	ds_write2_b32 v93, v1, v119 offset0:0 offset1:36
	s_nop 0
	v_add_f32_dpp v2, v118, v118 row_mirror row_mask:0xf bank_mask:0xf bound_ctrl:1
	v_add_f32_dpp v118, v118, v118 row_mirror row_mask:0xf bank_mask:0xf bound_ctrl:1
	s_nop 0
	s_waitcnt lgkmcnt(4)
	v_permlane16_swap_b32_e32 v118, v2
	v_add_f32_e32 v118, v118, v2
	v_pk_fma_f32 v[52:53], v[102:103], v[118:119], v[54:55] op_sel_hi:[1,0,1]
	v_pk_mul_f32 v[0:1], v[52:53], v[120:121] op_sel_hi:[0,1]
	v_pk_fma_f32 v[0:1], v[52:53], v[122:123], v[0:1] op_sel:[1,0,0]
	v_pk_mul_f32 v[126:127], v[110:111], v[126:127] op_sel_hi:[0,1]
	ds_read_b128 v[120:123], v90 offset:0x7a00
	v_add_f32_dpp v0, v0, v0 quad_perm:[1,0,3,2] row_mask:0xf bank_mask:0xf bound_ctrl:1
	v_add_f32_dpp v1, v1, v1 quad_perm:[1,0,3,2] row_mask:0xf bank_mask:0xf bound_ctrl:1
	v_pk_fma_f32 v[54:55], v[52:53], v[124:125], v[126:127]
	v_add_f32_dpp v0, v0, v0 quad_perm:[2,3,0,1] row_mask:0xf bank_mask:0xf bound_ctrl:1
	ds_read_b128 v[124:127], v90 offset:0x3a00
	s_nop 0
	v_add_f32_dpp v0, v0, v0 row_half_mirror row_mask:0xf bank_mask:0xf bound_ctrl:1
	ds_read2st64_b32 v[108:109], v89 offset0:220 offset1:221
	ds_read2st64_b64 v[100:103], v88 offset0:92 offset1:93
	v_add_f32_dpp v2, v0, v0 row_mirror row_mask:0xf bank_mask:0xf bound_ctrl:1
	v_add_f32_dpp v0, v0, v0 row_mirror row_mask:0xf bank_mask:0xf bound_ctrl:1
	s_nop 0
	s_waitcnt lgkmcnt(7)
	v_permlane16_swap_b32_e32 v0, v2
	v_add_f32_e32 v0, v0, v2
	v_pk_fma_f32 v[52:53], v[104:105], v[0:1], v[54:55] op_sel_hi:[1,0,1]
	v_pk_mul_f32 v[118:119], v[52:53], v[4:5] op_sel_hi:[0,1]
	v_pk_fma_f32 v[118:119], v[52:53], v[6:7], v[118:119] op_sel:[1,0,0]
	v_pk_mul_f32 v[10:11], v[110:111], v[10:11] op_sel:[1,0]
	ds_read_b128 v[4:7], v90 offset:0x7c00
	v_add_f32_dpp v118, v118, v118 quad_perm:[1,0,3,2] row_mask:0xf bank_mask:0xf bound_ctrl:1
	v_add_f32_dpp v119, v119, v119 quad_perm:[1,0,3,2] row_mask:0xf bank_mask:0xf bound_ctrl:1
	v_pk_fma_f32 v[54:55], v[52:53], v[8:9], v[10:11]
	v_add_f32_dpp v118, v118, v118 quad_perm:[2,3,0,1] row_mask:0xf bank_mask:0xf bound_ctrl:1
	ds_read_b128 v[8:11], v90 offset:0x3c00
	s_nop 0
	v_add_f32_dpp v118, v118, v118 row_half_mirror row_mask:0xf bank_mask:0xf bound_ctrl:1
	ds_write2_b32 v93, v1, v119 offset0:72 offset1:108
	s_nop 0
	v_add_f32_dpp v2, v118, v118 row_mirror row_mask:0xf bank_mask:0xf bound_ctrl:1
	v_add_f32_dpp v118, v118, v118 row_mirror row_mask:0xf bank_mask:0xf bound_ctrl:1
	s_nop 0
	s_waitcnt lgkmcnt(4)
	v_permlane16_swap_b32_e32 v118, v2
	v_add_f32_e32 v118, v118, v2
	v_pk_fma_f32 v[52:53], v[106:107], v[118:119], v[54:55] op_sel_hi:[1,0,1]
	v_pk_mul_f32 v[0:1], v[52:53], v[112:113] op_sel_hi:[0,1]
	v_pk_fma_f32 v[0:1], v[52:53], v[114:115], v[0:1] op_sel:[1,0,0]
	v_pk_mul_f32 v[98:99], v[108:109], v[98:99] op_sel_hi:[0,1]
	ds_read_b128 v[112:115], v90 offset:0x7e00
	v_add_f32_dpp v0, v0, v0 quad_perm:[1,0,3,2] row_mask:0xf bank_mask:0xf bound_ctrl:1
	v_add_f32_dpp v1, v1, v1 quad_perm:[1,0,3,2] row_mask:0xf bank_mask:0xf bound_ctrl:1
	v_pk_fma_f32 v[54:55], v[52:53], v[96:97], v[98:99]
	v_add_f32_dpp v0, v0, v0 quad_perm:[2,3,0,1] row_mask:0xf bank_mask:0xf bound_ctrl:1
	ds_read_b128 v[96:99], v90 offset:0x3e00
	s_nop 0
	v_add_f32_dpp v0, v0, v0 row_half_mirror row_mask:0xf bank_mask:0xf bound_ctrl:1
	ds_read2st64_b32 v[110:111], v89 offset0:222 offset1:223
	ds_read2st64_b64 v[104:107], v88 offset0:94 offset1:95
	v_add_f32_dpp v2, v0, v0 row_mirror row_mask:0xf bank_mask:0xf bound_ctrl:1
	v_add_f32_dpp v0, v0, v0 row_mirror row_mask:0xf bank_mask:0xf bound_ctrl:1
	s_nop 0
	s_waitcnt lgkmcnt(7)
	v_permlane16_swap_b32_e32 v0, v2
	v_add_f32_e32 v0, v0, v2
	v_pk_fma_f32 v[52:53], v[100:101], v[0:1], v[54:55] op_sel_hi:[1,0,1]
	v_pk_mul_f32 v[118:119], v[52:53], v[120:121] op_sel_hi:[0,1]
	v_pk_fma_f32 v[118:119], v[52:53], v[122:123], v[118:119] op_sel:[1,0,0]
	v_pk_mul_f32 v[126:127], v[108:109], v[126:127] op_sel:[1,0]
	s_nop 0
	v_add_f32_dpp v118, v118, v118 quad_perm:[1,0,3,2] row_mask:0xf bank_mask:0xf bound_ctrl:1
	v_add_f32_dpp v119, v119, v119 quad_perm:[1,0,3,2] row_mask:0xf bank_mask:0xf bound_ctrl:1
	v_pk_fma_f32 v[54:55], v[52:53], v[124:125], v[126:127]
	v_add_f32_dpp v118, v118, v118 quad_perm:[2,3,0,1] row_mask:0xf bank_mask:0xf bound_ctrl:1
	s_nop 0
	s_nop 0
	v_add_f32_dpp v118, v118, v118 row_half_mirror row_mask:0xf bank_mask:0xf bound_ctrl:1
	ds_write2_b32 v93, v1, v119 offset0:144 offset1:180
	s_nop 0
	v_add_f32_dpp v2, v118, v118 row_mirror row_mask:0xf bank_mask:0xf bound_ctrl:1
	v_add_f32_dpp v118, v118, v118 row_mirror row_mask:0xf bank_mask:0xf bound_ctrl:1
	s_nop 0
	s_waitcnt lgkmcnt(2)
	v_permlane16_swap_b32_e32 v118, v2
	v_add_f32_e32 v118, v118, v2
	v_pk_fma_f32 v[52:53], v[102:103], v[118:119], v[54:55] op_sel_hi:[1,0,1]
	v_pk_mul_f32 v[0:1], v[52:53], v[4:5] op_sel_hi:[0,1]
	v_pk_fma_f32 v[0:1], v[52:53], v[6:7], v[0:1] op_sel:[1,0,0]
	v_pk_mul_f32 v[10:11], v[110:111], v[10:11] op_sel_hi:[0,1]
	s_nop 0
	v_add_f32_dpp v0, v0, v0 quad_perm:[1,0,3,2] row_mask:0xf bank_mask:0xf bound_ctrl:1
	v_add_f32_dpp v1, v1, v1 quad_perm:[1,0,3,2] row_mask:0xf bank_mask:0xf bound_ctrl:1
	v_pk_fma_f32 v[54:55], v[52:53], v[8:9], v[10:11]
	v_add_f32_dpp v0, v0, v0 quad_perm:[2,3,0,1] row_mask:0xf bank_mask:0xf bound_ctrl:1
	s_nop 0
	s_nop 0
	v_add_f32_dpp v0, v0, v0 row_half_mirror row_mask:0xf bank_mask:0xf bound_ctrl:1
	s_nop 0
	s_nop 0
	v_add_f32_dpp v2, v0, v0 row_mirror row_mask:0xf bank_mask:0xf bound_ctrl:1
	v_add_f32_dpp v0, v0, v0 row_mirror row_mask:0xf bank_mask:0xf bound_ctrl:1
	s_nop 0
	s_waitcnt lgkmcnt(1)
	v_permlane16_swap_b32_e32 v0, v2
	v_add_f32_e32 v0, v0, v2
	v_pk_fma_f32 v[52:53], v[104:105], v[0:1], v[54:55] op_sel_hi:[1,0,1]
	v_pk_mul_f32 v[118:119], v[52:53], v[112:113] op_sel_hi:[0,1]
	v_pk_fma_f32 v[118:119], v[52:53], v[114:115], v[118:119] op_sel:[1,0,0]
	v_pk_mul_f32 v[98:99], v[110:111], v[98:99] op_sel:[1,0]
	s_nop 0
	v_add_f32_dpp v118, v118, v118 quad_perm:[1,0,3,2] row_mask:0xf bank_mask:0xf bound_ctrl:1
	v_add_f32_dpp v119, v119, v119 quad_perm:[1,0,3,2] row_mask:0xf bank_mask:0xf bound_ctrl:1
	v_pk_fma_f32 v[54:55], v[52:53], v[96:97], v[98:99]
	v_add_f32_dpp v118, v118, v118 quad_perm:[2,3,0,1] row_mask:0xf bank_mask:0xf bound_ctrl:1
	s_nop 0
	s_nop 0
	v_add_f32_dpp v118, v118, v118 row_half_mirror row_mask:0xf bank_mask:0xf bound_ctrl:1
	ds_write2_b32 v93, v1, v119 offset0:216 offset1:252
	s_nop 0
	v_add_f32_dpp v2, v118, v118 row_mirror row_mask:0xf bank_mask:0xf bound_ctrl:1
	v_add_f32_dpp v118, v118, v118 row_mirror row_mask:0xf bank_mask:0xf bound_ctrl:1
	s_nop 0
	s_nop 0
	v_permlane16_swap_b32_e32 v118, v2
	v_add_f32_e32 v118, v118, v2
	v_pk_fma_f32 v[52:53], v[106:107], v[118:119], v[54:55] op_sel_hi:[1,0,1]
